# adds hand-written last-layer residual epilogue (P7b) with 16B residual loads
# baseline (speedup 1.0000x reference)
.LBB0_1172:
	s_lshl_b32 s16, s43, 8
	s_add_i32 s16, s16, s35
	v_add_u32_e32 v146, s16, v158
	s_lshl_b32 s16, s42, 8
	s_or_b32 s16, s16, s36
	v_lshl_add_u32 v147, v159, 2, s16
	v_and_b32_e32 v148, 1, v159
	v_lshlrev_b32_e32 v149, 1, v147
	v_mad_u32_u24 v148, v148, 24, v149
	v_lshlrev_b32_e32 v149, 11, v146
	v_add_u32_e32 v142, v149, v148
	v_mov_b32_e32 v143, 0
	v_lshl_add_u64 v[142:143], v[142:143], 0, s[10:11]
	v_lshlrev_b32_e32 v149, 12, v146
	v_lshl_add_u32 v144, v147, 2, v149
	v_mov_b32_e32 v145, 0
	v_lshl_add_u64 v[144:145], v[144:145], 0, s[6:7]
	s_mov_b32 s17, 0
	global_load_dwordx4 v[162:165], v[142:143], off
	global_load_dwordx4 v[166:169], v[142:143], off offset:256
	s_mov_b32 s16, 0x8000
	v_lshl_add_u64 v[142:143], v[142:143], 0, s[16:17]
	global_load_dwordx4 v[170:173], v[142:143], off
	global_load_dwordx4 v[174:177], v[142:143], off offset:256
	s_mov_b32 s16, 0x8000
	v_lshl_add_u64 v[142:143], v[142:143], 0, s[16:17]
	global_load_dwordx4 v[178:181], v[142:143], off
	global_load_dwordx4 v[182:185], v[142:143], off offset:256
	s_mov_b32 s16, 0x8000
	v_lshl_add_u64 v[142:143], v[142:143], 0, s[16:17]
	global_load_dwordx4 v[186:189], v[142:143], off
	global_load_dwordx4 v[138:141], v[142:143], off offset:256
	s_mov_b32 s16, 0x28000
	v_lshl_add_u64 v[142:143], v[142:143], 0, s[16:17]
	s_waitcnt vmcnt(7)
	v_permlane16_swap_b32_e32 v162, v164
	v_permlane16_swap_b32_e32 v163, v165
	v_lshlrev_b32_e32 v148, 16, v162
	v_and_b32_e32 v149, 0xffff0000, v162
	v_add_f32_e32 v124, v124, v148
	v_add_f32_e32 v125, v125, v149
	v_lshlrev_b32_e32 v148, 16, v163
	v_and_b32_e32 v149, 0xffff0000, v163
	v_add_f32_e32 v126, v126, v148
	v_add_f32_e32 v127, v127, v149
	v_lshlrev_b32_e32 v148, 16, v164
	v_and_b32_e32 v149, 0xffff0000, v164
	v_add_f32_e32 v120, v120, v148
	v_add_f32_e32 v121, v121, v149
	v_lshlrev_b32_e32 v148, 16, v165
	v_and_b32_e32 v149, 0xffff0000, v165
	v_add_f32_e32 v122, v122, v148
	v_add_f32_e32 v123, v123, v149
	global_store_dwordx4 v[144:145], v[124:127], off
	global_store_dwordx4 v[144:145], v[120:123], off offset:64
	s_waitcnt vmcnt(8)
	v_permlane16_swap_b32_e32 v166, v168
	v_permlane16_swap_b32_e32 v167, v169
	v_lshlrev_b32_e32 v148, 16, v166
	v_and_b32_e32 v149, 0xffff0000, v166
	v_add_f32_e32 v116, v116, v148
	v_add_f32_e32 v117, v117, v149
	v_lshlrev_b32_e32 v148, 16, v167
	v_and_b32_e32 v149, 0xffff0000, v167
	v_add_f32_e32 v118, v118, v148
	v_add_f32_e32 v119, v119, v149
	v_lshlrev_b32_e32 v148, 16, v168
	v_and_b32_e32 v149, 0xffff0000, v168
	v_add_f32_e32 v108, v108, v148
	v_add_f32_e32 v109, v109, v149
	v_lshlrev_b32_e32 v148, 16, v169
	v_and_b32_e32 v149, 0xffff0000, v169
	v_add_f32_e32 v110, v110, v148
	v_add_f32_e32 v111, v111, v149
	global_store_dwordx4 v[144:145], v[116:119], off offset:512
	global_store_dwordx4 v[144:145], v[108:111], off offset:576
	s_nop 0
	s_mov_b32 s16, 0x10000
	v_lshl_add_u64 v[144:145], v[144:145], 0, s[16:17]
	s_waitcnt vmcnt(9)
	v_permlane16_swap_b32_e32 v170, v172
	v_permlane16_swap_b32_e32 v171, v173
	v_lshlrev_b32_e32 v148, 16, v170
	v_and_b32_e32 v149, 0xffff0000, v170
	v_add_f32_e32 v112, v112, v148
	v_add_f32_e32 v113, v113, v149
	v_lshlrev_b32_e32 v148, 16, v171
	v_and_b32_e32 v149, 0xffff0000, v171
	v_add_f32_e32 v114, v114, v148
	v_add_f32_e32 v115, v115, v149
	v_lshlrev_b32_e32 v148, 16, v172
	v_and_b32_e32 v149, 0xffff0000, v172
	v_add_f32_e32 v104, v104, v148
	v_add_f32_e32 v105, v105, v149
	v_lshlrev_b32_e32 v148, 16, v173
	v_and_b32_e32 v149, 0xffff0000, v173
	v_add_f32_e32 v106, v106, v148
	v_add_f32_e32 v107, v107, v149
	global_store_dwordx4 v[144:145], v[112:115], off
	global_store_dwordx4 v[144:145], v[104:107], off offset:64
	s_waitcnt vmcnt(10)
	v_permlane16_swap_b32_e32 v174, v176
	v_permlane16_swap_b32_e32 v175, v177
	v_lshlrev_b32_e32 v148, 16, v174
	v_and_b32_e32 v149, 0xffff0000, v174
	v_add_f32_e32 v100, v100, v148
	v_add_f32_e32 v101, v101, v149
	v_lshlrev_b32_e32 v148, 16, v175
	v_and_b32_e32 v149, 0xffff0000, v175
	v_add_f32_e32 v102, v102, v148
	v_add_f32_e32 v103, v103, v149
	v_lshlrev_b32_e32 v148, 16, v176
	v_and_b32_e32 v149, 0xffff0000, v176
	v_add_f32_e32 v88, v88, v148
	v_add_f32_e32 v89, v89, v149
	v_lshlrev_b32_e32 v148, 16, v177
	v_and_b32_e32 v149, 0xffff0000, v177
	v_add_f32_e32 v90, v90, v148
	v_add_f32_e32 v91, v91, v149
	global_store_dwordx4 v[144:145], v[100:103], off offset:512
	global_store_dwordx4 v[144:145], v[88:91], off offset:576
	s_nop 0
	s_mov_b32 s16, 0x10000
	v_lshl_add_u64 v[144:145], v[144:145], 0, s[16:17]
	s_waitcnt vmcnt(11)
	v_permlane16_swap_b32_e32 v178, v180
	v_permlane16_swap_b32_e32 v179, v181
	v_lshlrev_b32_e32 v148, 16, v178
	v_and_b32_e32 v149, 0xffff0000, v178
	v_add_f32_e32 v96, v96, v148
	v_add_f32_e32 v97, v97, v149
	v_lshlrev_b32_e32 v148, 16, v179
	v_and_b32_e32 v149, 0xffff0000, v179
	v_add_f32_e32 v98, v98, v148
	v_add_f32_e32 v99, v99, v149
	v_lshlrev_b32_e32 v148, 16, v180
	v_and_b32_e32 v149, 0xffff0000, v180
	v_add_f32_e32 v92, v92, v148
	v_add_f32_e32 v93, v93, v149
	v_lshlrev_b32_e32 v148, 16, v181
	v_and_b32_e32 v149, 0xffff0000, v181
	v_add_f32_e32 v94, v94, v148
	v_add_f32_e32 v95, v95, v149
	global_store_dwordx4 v[144:145], v[96:99], off
	global_store_dwordx4 v[144:145], v[92:95], off offset:64
	s_waitcnt vmcnt(12)
	v_permlane16_swap_b32_e32 v182, v184
	v_permlane16_swap_b32_e32 v183, v185
	v_lshlrev_b32_e32 v148, 16, v182
	v_and_b32_e32 v149, 0xffff0000, v182
	v_add_f32_e32 v80, v80, v148
	v_add_f32_e32 v81, v81, v149
	v_lshlrev_b32_e32 v148, 16, v183
	v_and_b32_e32 v149, 0xffff0000, v183
	v_add_f32_e32 v82, v82, v148
	v_add_f32_e32 v83, v83, v149
	v_lshlrev_b32_e32 v148, 16, v184
	v_and_b32_e32 v149, 0xffff0000, v184
	v_add_f32_e32 v72, v72, v148
	v_add_f32_e32 v73, v73, v149
	v_lshlrev_b32_e32 v148, 16, v185
	v_and_b32_e32 v149, 0xffff0000, v185
	v_add_f32_e32 v74, v74, v148
	v_add_f32_e32 v75, v75, v149
	global_store_dwordx4 v[144:145], v[80:83], off offset:512
	global_store_dwordx4 v[144:145], v[72:75], off offset:576
	s_nop 0
	s_mov_b32 s16, 0x10000
	v_lshl_add_u64 v[144:145], v[144:145], 0, s[16:17]
	s_waitcnt vmcnt(13)
	v_permlane16_swap_b32_e32 v186, v188
	v_permlane16_swap_b32_e32 v187, v189
	v_lshlrev_b32_e32 v148, 16, v186
	v_and_b32_e32 v149, 0xffff0000, v186
	v_add_f32_e32 v84, v84, v148
	v_add_f32_e32 v85, v85, v149
	v_lshlrev_b32_e32 v148, 16, v187
	v_and_b32_e32 v149, 0xffff0000, v187
	v_add_f32_e32 v86, v86, v148
	v_add_f32_e32 v87, v87, v149
	v_lshlrev_b32_e32 v148, 16, v188
	v_and_b32_e32 v149, 0xffff0000, v188
	v_add_f32_e32 v76, v76, v148
	v_add_f32_e32 v77, v77, v149
	v_lshlrev_b32_e32 v148, 16, v189
	v_and_b32_e32 v149, 0xffff0000, v189
	v_add_f32_e32 v78, v78, v148
	v_add_f32_e32 v79, v79, v149
	global_store_dwordx4 v[144:145], v[84:87], off
	global_store_dwordx4 v[144:145], v[76:79], off offset:64
	s_waitcnt vmcnt(14)
	v_permlane16_swap_b32_e32 v138, v140
	v_permlane16_swap_b32_e32 v139, v141
	v_lshlrev_b32_e32 v148, 16, v138
	v_and_b32_e32 v149, 0xffff0000, v138
	v_add_f32_e32 v68, v68, v148
	v_add_f32_e32 v69, v69, v149
	v_lshlrev_b32_e32 v148, 16, v139
	v_and_b32_e32 v149, 0xffff0000, v139
	v_add_f32_e32 v70, v70, v148
	v_add_f32_e32 v71, v71, v149
	v_lshlrev_b32_e32 v148, 16, v140
	v_and_b32_e32 v149, 0xffff0000, v140
	v_add_f32_e32 v64, v64, v148
	v_add_f32_e32 v65, v65, v149
	v_lshlrev_b32_e32 v148, 16, v141
	v_and_b32_e32 v149, 0xffff0000, v141
	v_add_f32_e32 v66, v66, v148
	v_add_f32_e32 v67, v67, v149
	global_store_dwordx4 v[144:145], v[68:71], off offset:512
	global_store_dwordx4 v[144:145], v[64:67], off offset:576
	s_nop 0
	s_mov_b32 s16, 0x50000
	v_lshl_add_u64 v[144:145], v[144:145], 0, s[16:17]
	global_load_dwordx4 v[162:165], v[142:143], off
	global_load_dwordx4 v[166:169], v[142:143], off offset:256
	s_mov_b32 s16, 0x8000
	v_lshl_add_u64 v[142:143], v[142:143], 0, s[16:17]
	global_load_dwordx4 v[170:173], v[142:143], off
	global_load_dwordx4 v[174:177], v[142:143], off offset:256
	s_mov_b32 s16, 0x8000
	v_lshl_add_u64 v[142:143], v[142:143], 0, s[16:17]
	global_load_dwordx4 v[178:181], v[142:143], off
	global_load_dwordx4 v[182:185], v[142:143], off offset:256
	s_mov_b32 s16, 0x8000
	v_lshl_add_u64 v[142:143], v[142:143], 0, s[16:17]
	global_load_dwordx4 v[186:189], v[142:143], off
	global_load_dwordx4 v[138:141], v[142:143], off offset:256
	s_waitcnt vmcnt(7)
	v_permlane16_swap_b32_e32 v162, v164
	v_permlane16_swap_b32_e32 v163, v165
	v_lshlrev_b32_e32 v148, 16, v162
	v_and_b32_e32 v149, 0xffff0000, v162
	v_add_f32_e32 v60, v60, v148
	v_add_f32_e32 v61, v61, v149
	v_lshlrev_b32_e32 v148, 16, v163
	v_and_b32_e32 v149, 0xffff0000, v163
	v_add_f32_e32 v62, v62, v148
	v_add_f32_e32 v63, v63, v149
	v_lshlrev_b32_e32 v148, 16, v164
	v_and_b32_e32 v149, 0xffff0000, v164
	v_add_f32_e32 v56, v56, v148
	v_add_f32_e32 v57, v57, v149
	v_lshlrev_b32_e32 v148, 16, v165
	v_and_b32_e32 v149, 0xffff0000, v165
	v_add_f32_e32 v58, v58, v148
	v_add_f32_e32 v59, v59, v149
	global_store_dwordx4 v[144:145], v[60:63], off
	global_store_dwordx4 v[144:145], v[56:59], off offset:64
	s_waitcnt vmcnt(8)
	v_permlane16_swap_b32_e32 v166, v168
	v_permlane16_swap_b32_e32 v167, v169
	v_lshlrev_b32_e32 v148, 16, v166
	v_and_b32_e32 v149, 0xffff0000, v166
	v_add_f32_e32 v48, v48, v148
	v_add_f32_e32 v49, v49, v149
	v_lshlrev_b32_e32 v148, 16, v167
	v_and_b32_e32 v149, 0xffff0000, v167
	v_add_f32_e32 v50, v50, v148
	v_add_f32_e32 v51, v51, v149
	v_lshlrev_b32_e32 v148, 16, v168
	v_and_b32_e32 v149, 0xffff0000, v168
	v_add_f32_e32 v40, v40, v148
	v_add_f32_e32 v41, v41, v149
	v_lshlrev_b32_e32 v148, 16, v169
	v_and_b32_e32 v149, 0xffff0000, v169
	v_add_f32_e32 v42, v42, v148
	v_add_f32_e32 v43, v43, v149
	global_store_dwordx4 v[144:145], v[48:51], off offset:512
	global_store_dwordx4 v[144:145], v[40:43], off offset:576
	s_nop 0
	s_mov_b32 s16, 0x10000
	v_lshl_add_u64 v[144:145], v[144:145], 0, s[16:17]
	s_waitcnt vmcnt(9)
	v_permlane16_swap_b32_e32 v170, v172
	v_permlane16_swap_b32_e32 v171, v173
	v_lshlrev_b32_e32 v148, 16, v170
	v_and_b32_e32 v149, 0xffff0000, v170
	v_add_f32_e32 v52, v52, v148
	v_add_f32_e32 v53, v53, v149
	v_lshlrev_b32_e32 v148, 16, v171
	v_and_b32_e32 v149, 0xffff0000, v171
	v_add_f32_e32 v54, v54, v148
	v_add_f32_e32 v55, v55, v149
	v_lshlrev_b32_e32 v148, 16, v172
	v_and_b32_e32 v149, 0xffff0000, v172
	v_add_f32_e32 v44, v44, v148
	v_add_f32_e32 v45, v45, v149
	v_lshlrev_b32_e32 v148, 16, v173
	v_and_b32_e32 v149, 0xffff0000, v173
	v_add_f32_e32 v46, v46, v148
	v_add_f32_e32 v47, v47, v149
	global_store_dwordx4 v[144:145], v[52:55], off
	global_store_dwordx4 v[144:145], v[44:47], off offset:64
	s_waitcnt vmcnt(10)
	v_permlane16_swap_b32_e32 v174, v176
	v_permlane16_swap_b32_e32 v175, v177
	v_lshlrev_b32_e32 v148, 16, v174
	v_and_b32_e32 v149, 0xffff0000, v174
	v_add_f32_e32 v32, v32, v148
	v_add_f32_e32 v33, v33, v149
	v_lshlrev_b32_e32 v148, 16, v175
	v_and_b32_e32 v149, 0xffff0000, v175
	v_add_f32_e32 v34, v34, v148
	v_add_f32_e32 v35, v35, v149
	v_lshlrev_b32_e32 v148, 16, v176
	v_and_b32_e32 v149, 0xffff0000, v176
	v_add_f32_e32 v24, v24, v148
	v_add_f32_e32 v25, v25, v149
	v_lshlrev_b32_e32 v148, 16, v177
	v_and_b32_e32 v149, 0xffff0000, v177
	v_add_f32_e32 v26, v26, v148
	v_add_f32_e32 v27, v27, v149
	global_store_dwordx4 v[144:145], v[32:35], off offset:512
	global_store_dwordx4 v[144:145], v[24:27], off offset:576
	s_nop 0
	s_mov_b32 s16, 0x10000
	v_lshl_add_u64 v[144:145], v[144:145], 0, s[16:17]
	s_waitcnt vmcnt(11)
	v_permlane16_swap_b32_e32 v178, v180
	v_permlane16_swap_b32_e32 v179, v181
	v_lshlrev_b32_e32 v148, 16, v178
	v_and_b32_e32 v149, 0xffff0000, v178
	v_add_f32_e32 v36, v36, v148
	v_add_f32_e32 v37, v37, v149
	v_lshlrev_b32_e32 v148, 16, v179
	v_and_b32_e32 v149, 0xffff0000, v179
	v_add_f32_e32 v38, v38, v148
	v_add_f32_e32 v39, v39, v149
	v_lshlrev_b32_e32 v148, 16, v180
	v_and_b32_e32 v149, 0xffff0000, v180
	v_add_f32_e32 v28, v28, v148
	v_add_f32_e32 v29, v29, v149
	v_lshlrev_b32_e32 v148, 16, v181
	v_and_b32_e32 v149, 0xffff0000, v181
	v_add_f32_e32 v30, v30, v148
	v_add_f32_e32 v31, v31, v149
	global_store_dwordx4 v[144:145], v[36:39], off
	global_store_dwordx4 v[144:145], v[28:31], off offset:64
	s_waitcnt vmcnt(12)
	v_permlane16_swap_b32_e32 v182, v184
	v_permlane16_swap_b32_e32 v183, v185
	v_lshlrev_b32_e32 v148, 16, v182
	v_and_b32_e32 v149, 0xffff0000, v182
	v_add_f32_e32 v16, v16, v148
	v_add_f32_e32 v17, v17, v149
	v_lshlrev_b32_e32 v148, 16, v183
	v_and_b32_e32 v149, 0xffff0000, v183
	v_add_f32_e32 v18, v18, v148
	v_add_f32_e32 v19, v19, v149
	v_lshlrev_b32_e32 v148, 16, v184
	v_and_b32_e32 v149, 0xffff0000, v184
	v_add_f32_e32 v8, v8, v148
	v_add_f32_e32 v9, v9, v149
	v_lshlrev_b32_e32 v148, 16, v185
	v_and_b32_e32 v149, 0xffff0000, v185
	v_add_f32_e32 v10, v10, v148
	v_add_f32_e32 v11, v11, v149
	global_store_dwordx4 v[144:145], v[16:19], off offset:512
	global_store_dwordx4 v[144:145], v[8:11], off offset:576
	s_nop 0
	s_mov_b32 s16, 0x10000
	v_lshl_add_u64 v[144:145], v[144:145], 0, s[16:17]
	s_waitcnt vmcnt(13)
	v_permlane16_swap_b32_e32 v186, v188
	v_permlane16_swap_b32_e32 v187, v189
	v_lshlrev_b32_e32 v148, 16, v186
	v_and_b32_e32 v149, 0xffff0000, v186
	v_add_f32_e32 v20, v20, v148
	v_add_f32_e32 v21, v21, v149
	v_lshlrev_b32_e32 v148, 16, v187
	v_and_b32_e32 v149, 0xffff0000, v187
	v_add_f32_e32 v22, v22, v148
	v_add_f32_e32 v23, v23, v149
	v_lshlrev_b32_e32 v148, 16, v188
	v_and_b32_e32 v149, 0xffff0000, v188
	v_add_f32_e32 v12, v12, v148
	v_add_f32_e32 v13, v13, v149
	v_lshlrev_b32_e32 v148, 16, v189
	v_and_b32_e32 v149, 0xffff0000, v189
	v_add_f32_e32 v14, v14, v148
	v_add_f32_e32 v15, v15, v149
	global_store_dwordx4 v[144:145], v[20:23], off
	global_store_dwordx4 v[144:145], v[12:15], off offset:64
	s_waitcnt vmcnt(14)
	v_permlane16_swap_b32_e32 v138, v140
	v_permlane16_swap_b32_e32 v139, v141
	v_lshlrev_b32_e32 v148, 16, v138
	v_and_b32_e32 v149, 0xffff0000, v138
	v_add_f32_e32 v4, v4, v148
	v_add_f32_e32 v5, v5, v149
	v_lshlrev_b32_e32 v148, 16, v139
	v_and_b32_e32 v149, 0xffff0000, v139
	v_add_f32_e32 v6, v6, v148
	v_add_f32_e32 v7, v7, v149
	v_lshlrev_b32_e32 v148, 16, v140
	v_and_b32_e32 v149, 0xffff0000, v140
	v_add_f32_e32 v0, v0, v148
	v_add_f32_e32 v1, v1, v149
	v_lshlrev_b32_e32 v148, 16, v141
	v_and_b32_e32 v149, 0xffff0000, v141
	v_add_f32_e32 v2, v2, v148
	v_add_f32_e32 v3, v3, v149
	global_store_dwordx4 v[144:145], v[4:7], off offset:512
	global_store_dwordx4 v[144:145], v[0:3], off offset:576
	s_mov_b64 s[16:17], -1
	s_and_b64 vcc, exec, s[0:1]
	s_cbranch_vccnz .LBB0_1157
	s_andn2_b64 vcc, exec, s[4:5]
	s_cbranch_vccnz .LBB0_1156
	s_barrier
	s_branch .LBB0_1156
